# speedup vs baseline: 1.0098x; 1.0048x over previous
; template <int EPI>
; __device__ __forceinline__ void gemm_phase(const Params& p, const u16* __restrict__ A, const u16* __restrict__ Bt, int K, int nN,
;                            u16* __restrict__ Cout, int ldc) {
;     ...
; #pragma unroll
;       for (int half = 0; half < 2; ++half) {
; #pragma unroll
;         for (int mm = 0; mm < 4; ++mm) {
;           const int m = half * 4 + mm;
; #pragma unroll
;           for (int j = 0; j < 4; ++j) {
;             float rs = 1.f;
;             if (EPI == EPI_WIN) rs = rsl[wr * 128 + m * 16 + fqe * 4 + j];
;             u16* d = stg + (wr * 64 + mm * 16 + fqe * 4 + j) * 256 + (fre & 7);
; #pragma unroll
;             for (int n = 0; n < 4; ++n) {
;               const int chunk = (wc * 8 + n * 2 + (fre >> 3)) ^ (fqe << 1);
;               d[chunk * 8] = f2bf(acc[m][n][j] * rs);
;             }
;           }
;           __builtin_amdgcn_sched_barrier(0);
;         }
;         __syncthreads();
.LBB0_854:
	v_mov_b32_e32 v136, v192
	v_mov_b32_e32 v137, v173
	v_mov_b32_e32 v128, v174
	s_nop 0
	v_lshlrev_b32_e32 v138, 4, v136
	v_add_u32_e32 v131, v196, v138
	ds_read_b128 v[132:135], v131
	v_and_b32_e32 v139, 7, v128
	v_add_u32_e32 v140, v128, v197
	v_lshlrev_b32_e32 v136, 11, v136
	v_lshlrev_b32_e32 v139, 1, v139
	s_waitcnt lgkmcnt(0)
	v_mul_f32_e32 v124, v124, v132
	v_add3_u32 v136, v205, v139, v136
	v_cvt_pk_bf16_f32 v139, v124, s0
	v_bitop3_b32 v124, v140, v138, -8 bitop3:0x6c
	v_and_b32_e32 v143, -8, v140
	v_lshl_add_u32 v124, v124, 1, v136
	v_mul_f32_e32 v120, v120, v132
	ds_write_b16 v124, v139
	v_cvt_pk_bf16_f32 v139, v120, s0
	v_add_u32_e32 v120, 16, v143
	v_xor_b32_e32 v120, v120, v138
	v_lshl_add_u32 v120, v120, 1, v136
	v_mul_f32_e32 v116, v116, v132
	v_mul_f32_e32 v112, v112, v132
	ds_write_b16 v120, v139
	v_cvt_pk_bf16_f32 v139, v116, s0
	v_add_u32_e32 v116, 32, v143
	v_cvt_pk_bf16_f32 v132, v112, s0
	v_add_u32_e32 v112, 48, v143
	v_xor_b32_e32 v116, v116, v138
	v_xor_b32_e32 v112, v112, v138
	v_mul_f32_e32 v113, v113, v133
	v_lshl_add_u32 v116, v116, 1, v136
	v_lshl_add_u32 v112, v112, 1, v136
	v_cvt_pk_bf16_f32 v113, v113, s0
	ds_write_b16 v116, v139
	v_mul_f32_e32 v121, v121, v133
	v_mul_f32_e32 v117, v117, v133
	ds_write_b16 v112, v113 offset:512
	v_mul_f32_e32 v113, v126, v134
	v_cvt_pk_bf16_f32 v121, v121, s0
	v_cvt_pk_bf16_f32 v117, v117, s0
	v_cvt_pk_bf16_f32 v113, v113, s0
	ds_write_b16 v112, v132
	v_mul_f32_e32 v125, v125, v133
	ds_write_b16 v120, v121 offset:512
	ds_write_b16 v116, v117 offset:512
	ds_write_b16 v124, v113 offset:1024
	v_mul_f32_e32 v113, v122, v134
	v_cvt_pk_bf16_f32 v125, v125, s0
	v_cvt_pk_bf16_f32 v113, v113, s0
	ds_write_b16 v124, v125 offset:512
	ds_write_b16 v120, v113 offset:1024
	v_mul_f32_e32 v113, v118, v134
	v_cvt_pk_bf16_f32 v113, v113, s0
	ds_write_b16 v116, v113 offset:1024
	v_mul_f32_e32 v113, v114, v134
	v_cvt_pk_bf16_f32 v113, v113, s0
	ds_write_b16 v112, v113 offset:1024
	v_mul_f32_e32 v113, v127, v135
	v_cvt_pk_bf16_f32 v113, v113, s0
	ds_write_b16 v124, v113 offset:1536
	v_mul_f32_e32 v113, v123, v135
	v_cvt_pk_bf16_f32 v113, v113, s0
	ds_write_b16 v120, v113 offset:1536
	v_mul_f32_e32 v113, v119, v135
	v_and_b32_e32 v128, 31, v137
	v_lshrrev_b32_e32 v129, 6, v137
	v_cvt_pk_bf16_f32 v113, v113, s0
	v_bitop3_b32 v129, v129, v128, 6 bitop3:0x6c
	ds_write_b16 v116, v113 offset:1536
	v_mul_f32_e32 v113, v115, v135
	v_lshl_or_b32 v141, v129, 4, v188
	v_lshl_or_b32 v128, v128, 3, s18
	v_mov_b32_e32 v129, v172
	v_ashrrev_i32_e32 v142, 5, v137
	v_cvt_pk_bf16_f32 v113, v113, s0
	v_lshl_add_u64 v[128:129], v[128:129], 1, s[10:11]
	v_lshl_add_u32 v130, v142, 9, v141
	ds_write_b16 v112, v113 offset:1536
	ds_read_b128 v[132:135], v131 offset:64
	s_waitcnt lgkmcnt(0)
	v_mul_f32_e32 v108, v108, v132
	v_mul_f32_e32 v96, v96, v132
	v_mul_f32_e32 v104, v104, v132
	v_cvt_pk_bf16_f32 v108, v108, s0
	v_cvt_pk_bf16_f32 v96, v96, s0
	v_mul_f32_e32 v100, v100, v132
	v_cvt_pk_bf16_f32 v104, v104, s0
	ds_write_b16 v124, v108 offset:8192
	ds_write_b16 v120, v104 offset:8192
	ds_write_b16 v112, v96 offset:8192
	v_mul_f32_e32 v96, v109, v133
	v_cvt_pk_bf16_f32 v100, v100, s0
	v_cvt_pk_bf16_f32 v96, v96, s0
	ds_write_b16 v116, v100 offset:8192
	ds_write_b16 v124, v96 offset:8704
	v_mul_f32_e32 v96, v105, v133
	v_cvt_pk_bf16_f32 v96, v96, s0
	ds_write_b16 v120, v96 offset:8704
	v_mul_f32_e32 v96, v101, v133
	v_cvt_pk_bf16_f32 v96, v96, s0
	ds_write_b16 v116, v96 offset:8704
	v_mul_f32_e32 v96, v97, v133
	v_cvt_pk_bf16_f32 v96, v96, s0
	ds_write_b16 v112, v96 offset:8704
	v_mul_f32_e32 v96, v110, v134
	v_cvt_pk_bf16_f32 v96, v96, s0
	ds_write_b16 v124, v96 offset:9216
	v_mul_f32_e32 v96, v106, v134
	v_cvt_pk_bf16_f32 v96, v96, s0
	ds_write_b16 v120, v96 offset:9216
	v_mul_f32_e32 v96, v102, v134
	v_cvt_pk_bf16_f32 v96, v96, s0
	ds_write_b16 v116, v96 offset:9216
	v_mul_f32_e32 v96, v98, v134
	v_cvt_pk_bf16_f32 v96, v96, s0
	ds_write_b16 v112, v96 offset:9216
	v_mul_f32_e32 v96, v111, v135
	v_cvt_pk_bf16_f32 v96, v96, s0
	ds_write_b16 v124, v96 offset:9728
	v_mul_f32_e32 v96, v107, v135
	v_cvt_pk_bf16_f32 v96, v96, s0
	ds_write_b16 v120, v96 offset:9728
	v_mul_f32_e32 v96, v103, v135
	v_cvt_pk_bf16_f32 v96, v96, s0
	ds_write_b16 v116, v96 offset:9728
	v_mul_f32_e32 v96, v99, v135
	v_cvt_pk_bf16_f32 v96, v96, s0
	ds_write_b16 v112, v96 offset:9728
	ds_read_b128 v[96:99], v131 offset:128
	s_waitcnt lgkmcnt(0)
	v_mul_f32_e32 v92, v92, v96
	v_mul_f32_e32 v80, v80, v96
	v_mul_f32_e32 v88, v88, v96
	v_cvt_pk_bf16_f32 v92, v92, s0
	v_cvt_pk_bf16_f32 v80, v80, s0
	v_mul_f32_e32 v84, v84, v96
	v_cvt_pk_bf16_f32 v88, v88, s0
	ds_write_b16 v124, v92 offset:16384
	ds_write_b16 v120, v88 offset:16384
	ds_write_b16 v112, v80 offset:16384
	v_mul_f32_e32 v80, v93, v97
	v_cvt_pk_bf16_f32 v84, v84, s0
	v_cvt_pk_bf16_f32 v80, v80, s0
	ds_write_b16 v116, v84 offset:16384
	ds_write_b16 v124, v80 offset:16896
	v_mul_f32_e32 v80, v89, v97
	v_cvt_pk_bf16_f32 v80, v80, s0
	ds_write_b16 v120, v80 offset:16896
	v_mul_f32_e32 v80, v85, v97
	v_cvt_pk_bf16_f32 v80, v80, s0
	ds_write_b16 v116, v80 offset:16896
	v_mul_f32_e32 v80, v81, v97
	v_cvt_pk_bf16_f32 v80, v80, s0
	ds_write_b16 v112, v80 offset:16896
	v_mul_f32_e32 v80, v94, v98
	v_cvt_pk_bf16_f32 v80, v80, s0
	ds_write_b16 v124, v80 offset:17408
	v_mul_f32_e32 v80, v90, v98
	v_cvt_pk_bf16_f32 v80, v80, s0
	ds_write_b16 v120, v80 offset:17408
	v_mul_f32_e32 v80, v86, v98
	v_cvt_pk_bf16_f32 v80, v80, s0
	ds_write_b16 v116, v80 offset:17408
	v_mul_f32_e32 v80, v82, v98
	v_cvt_pk_bf16_f32 v80, v80, s0
	ds_write_b16 v112, v80 offset:17408
	v_mul_f32_e32 v80, v95, v99
	v_cvt_pk_bf16_f32 v80, v80, s0
	ds_write_b16 v124, v80 offset:17920
	v_mul_f32_e32 v80, v91, v99
	v_cvt_pk_bf16_f32 v80, v80, s0
	ds_write_b16 v120, v80 offset:17920
	v_mul_f32_e32 v80, v87, v99
	v_cvt_pk_bf16_f32 v80, v80, s0
	ds_write_b16 v116, v80 offset:17920
	v_mul_f32_e32 v80, v83, v99
	v_cvt_pk_bf16_f32 v80, v80, s0
	ds_write_b16 v112, v80 offset:17920
	ds_read_b128 v[80:83], v131 offset:192
	s_waitcnt lgkmcnt(0)
; template <int EPI>
; __device__ __forceinline__ void gemm_phase(const Params& p, const u16* __restrict__ A, const u16* __restrict__ Bt, int K, int nN,
;                            u16* __restrict__ Cout, int ldc) {
;     ...
;           for (int j = 0; j < 4; ++j) {
;             float rs = 1.f;
;             if (EPI == EPI_WIN) rs = rsl[wr * 128 + m * 16 + fqe * 4 + j];
;             u16* d = stg + (wr * 64 + mm * 16 + fqe * 4 + j) * 256 + (fre & 7);
; #pragma unroll
;             for (int n = 0; n < 4; ++n) {
;               const int chunk = (wc * 8 + n * 2 + (fre >> 3)) ^ (fqe << 1);
;               d[chunk * 8] = f2bf(acc[m][n][j] * rs);
;             }
;           }
;           __builtin_amdgcn_sched_barrier(0);
;         }
;         __syncthreads();
; #pragma unroll
;         for (int it = 0; it < 8; ++it) {
;           const int id = it * 512 + tide, r = id >> 5, ck = id & 31;
;           const uint4 v = *(const uint4*)(stg + r * 256 + ((ck ^ (((r >> 2) & 3) << 1)) * 8));
;           const int grow = brow + (r >> 6) * 128 + half * 64 + (r & 63);
;           if (EPI == EPI_WIN) { typedef __attribute__((ext_vector_type(4))) unsigned u32x4_; const u32x4_ t_ = {v.x, v.y, v.z, v.w};
;             __builtin_nontemporal_store(t_, (u32x4_*)(Cout + (unsigned)grow * (unsigned)ldc + (unsigned)(bcol + ck * 8))); }
;           else *(uint4*)(Cout + (unsigned)grow * (unsigned)ldc + (unsigned)(bcol + ck * 8)) = v;
;         }
;         asm volatile("s_waitcnt lgkmcnt(0)" ::: "memory"); __builtin_amdgcn_s_barrier();
	v_mul_f32_e32 v76, v76, v80
	v_mul_f32_e32 v64, v64, v80
	v_mul_f32_e32 v72, v72, v80
	v_cvt_pk_bf16_f32 v76, v76, s0
	v_cvt_pk_bf16_f32 v64, v64, s0
	v_mul_f32_e32 v68, v68, v80
	v_cvt_pk_bf16_f32 v72, v72, s0
	ds_write_b16 v124, v76 offset:24576
	ds_write_b16 v120, v72 offset:24576
	ds_write_b16 v112, v64 offset:24576
	v_mul_f32_e32 v64, v77, v81
	v_cvt_pk_bf16_f32 v68, v68, s0
	v_cvt_pk_bf16_f32 v64, v64, s0
	ds_write_b16 v116, v68 offset:24576
	ds_write_b16 v124, v64 offset:25088
	v_mul_f32_e32 v64, v73, v81
	v_cvt_pk_bf16_f32 v64, v64, s0
	ds_write_b16 v120, v64 offset:25088
	v_mul_f32_e32 v64, v69, v81
	v_cvt_pk_bf16_f32 v64, v64, s0
	ds_write_b16 v116, v64 offset:25088
	v_mul_f32_e32 v64, v65, v81
	v_cvt_pk_bf16_f32 v64, v64, s0
	ds_write_b16 v112, v64 offset:25088
	v_mul_f32_e32 v64, v78, v82
	v_cvt_pk_bf16_f32 v64, v64, s0
	ds_write_b16 v124, v64 offset:25600
	v_mul_f32_e32 v64, v74, v82
	v_cvt_pk_bf16_f32 v64, v64, s0
	ds_write_b16 v120, v64 offset:25600
	v_mul_f32_e32 v64, v70, v82
	v_cvt_pk_bf16_f32 v64, v64, s0
	ds_write_b16 v116, v64 offset:25600
	v_mul_f32_e32 v64, v66, v82
	v_cvt_pk_bf16_f32 v64, v64, s0
	ds_write_b16 v112, v64 offset:25600
	v_mul_f32_e32 v64, v79, v83
	v_cvt_pk_bf16_f32 v64, v64, s0
	ds_write_b16 v124, v64 offset:26112
	v_mul_f32_e32 v64, v75, v83
	v_cvt_pk_bf16_f32 v64, v64, s0
	ds_write_b16 v120, v64 offset:26112
	v_mul_f32_e32 v64, v71, v83
	v_cvt_pk_bf16_f32 v64, v64, s0
	ds_write_b16 v116, v64 offset:26112
	v_mul_f32_e32 v64, v67, v83
	v_cvt_pk_bf16_f32 v64, v64, s0
	ds_write_b16 v112, v64 offset:26112
	v_ashrrev_i32_e32 v68, 4, v137
	s_waitcnt lgkmcnt(0)
	s_barrier
	ds_read_b128 v[212:215], v130
	v_add_u32_e32 v244, 0x200, v137
	v_ashrrev_i32_e32 v245, 5, v244
	v_lshl_add_u32 v244, v245, 9, v141
	ds_read_b128 v[216:219], v244
	v_add_u32_e32 v244, 0x400, v137
	v_ashrrev_i32_e32 v245, 5, v244
	v_lshl_add_u32 v244, v245, 9, v141
	ds_read_b128 v[220:223], v244
	v_add_u32_e32 v244, 0x600, v137
	v_ashrrev_i32_e32 v245, 5, v244
	v_lshl_add_u32 v244, v245, 9, v141
	ds_read_b128 v[224:227], v244
	v_add_u32_e32 v244, 0x800, v137
	v_ashrrev_i32_e32 v245, 5, v244
	v_lshl_add_u32 v244, v245, 9, v141
	ds_read_b128 v[228:231], v244
	v_add_u32_e32 v244, 0xa00, v137
	v_ashrrev_i32_e32 v245, 5, v244
	v_lshl_add_u32 v244, v245, 9, v141
	ds_read_b128 v[232:235], v244
	v_add_u32_e32 v244, 0xc00, v137
	v_ashrrev_i32_e32 v245, 5, v244
	v_lshl_add_u32 v244, v245, 9, v141
	ds_read_b128 v[236:239], v244
	v_add_u32_e32 v244, 0xe00, v137
	v_ashrrev_i32_e32 v245, 5, v244
	v_lshl_add_u32 v244, v245, 9, v141
	ds_read_b128 v[240:243], v244
	v_and_b32_e32 v70, 0xffffff80, v68
	v_add_u32_e32 v68, s16, v70
	v_and_b32_e32 v71, 63, v142
	v_or_b32_e32 v68, v68, v71
	v_mul_lo_u32 v68, v68, s58
	v_mov_b32_e32 v69, v172
	v_lshl_add_u64 v[68:69], v[68:69], 1, v[128:129]
	s_waitcnt lgkmcnt(7)
	global_store_dwordx4 v[68:69], v[212:215], off nt
	v_add_u32_e32 v68, 0x200, v137
	v_ashrrev_i32_e32 v69, 5, v68
	v_lshl_add_u32 v72, v69, 9, v141
	v_ashrrev_i32_e32 v68, 4, v68
	v_and_b32_e32 v73, 0xffffff80, v68
	v_add_u32_e32 v68, s16, v73
	v_and_b32_e32 v74, 63, v69
	v_or_b32_e32 v68, v68, v74
	v_mul_lo_u32 v68, v68, s58
	v_mov_b32_e32 v69, v172
	v_lshl_add_u64 v[68:69], v[68:69], 1, v[128:129]
	s_waitcnt lgkmcnt(6)
	global_store_dwordx4 v[68:69], v[216:219], off nt
	v_add_u32_e32 v68, 0x400, v137
	v_ashrrev_i32_e32 v69, 5, v68
	v_lshl_add_u32 v75, v69, 9, v141
	v_ashrrev_i32_e32 v68, 4, v68
	v_and_b32_e32 v76, 0xffffff80, v68
	v_add_u32_e32 v68, s16, v76
	v_and_b32_e32 v77, 63, v69
	v_or_b32_e32 v68, v68, v77
	v_mul_lo_u32 v68, v68, s58
	v_mov_b32_e32 v69, v172
	v_lshl_add_u64 v[68:69], v[68:69], 1, v[128:129]
	s_waitcnt lgkmcnt(5)
	global_store_dwordx4 v[68:69], v[220:223], off nt
	v_add_u32_e32 v68, 0x600, v137
	v_ashrrev_i32_e32 v69, 5, v68
	v_lshl_add_u32 v78, v69, 9, v141
	v_ashrrev_i32_e32 v68, 4, v68
	v_and_b32_e32 v79, 0xffffff80, v68
	v_add_u32_e32 v68, s16, v79
	v_and_b32_e32 v80, 63, v69
	v_or_b32_e32 v68, v68, v80
	v_mul_lo_u32 v68, v68, s58
	v_mov_b32_e32 v69, v172
	v_lshl_add_u64 v[68:69], v[68:69], 1, v[128:129]
	s_waitcnt lgkmcnt(4)
	global_store_dwordx4 v[68:69], v[224:227], off nt
	v_add_u32_e32 v68, 0x800, v137
	v_ashrrev_i32_e32 v69, 5, v68
	v_lshl_add_u32 v81, v69, 9, v141
	v_ashrrev_i32_e32 v68, 4, v68
	v_and_b32_e32 v82, 0xffffff80, v68
	v_add_u32_e32 v68, s16, v82
	v_and_b32_e32 v83, 63, v69
	v_or_b32_e32 v68, v68, v83
	v_mul_lo_u32 v68, v68, s58
	v_mov_b32_e32 v69, v172
	v_lshl_add_u64 v[68:69], v[68:69], 1, v[128:129]
	s_waitcnt lgkmcnt(3)
	global_store_dwordx4 v[68:69], v[228:231], off nt
	v_add_u32_e32 v68, 0xa00, v137
	v_ashrrev_i32_e32 v69, 5, v68
	v_lshl_add_u32 v84, v69, 9, v141
	v_ashrrev_i32_e32 v68, 4, v68
	v_and_b32_e32 v85, 0xffffff80, v68
	v_add_u32_e32 v68, s16, v85
	v_and_b32_e32 v86, 63, v69
	v_or_b32_e32 v68, v68, v86
	v_mul_lo_u32 v68, v68, s58
	v_mov_b32_e32 v69, v172
	v_lshl_add_u64 v[68:69], v[68:69], 1, v[128:129]
	s_waitcnt lgkmcnt(2)
	global_store_dwordx4 v[68:69], v[232:235], off nt
	v_add_u32_e32 v68, 0xc00, v137
	v_ashrrev_i32_e32 v69, 5, v68
	v_lshl_add_u32 v87, v69, 9, v141
	v_ashrrev_i32_e32 v68, 4, v68
	v_and_b32_e32 v88, 0xffffff80, v68
	v_add_u32_e32 v68, s16, v88
	v_and_b32_e32 v89, 63, v69
	v_or_b32_e32 v68, v68, v89
	v_mul_lo_u32 v68, v68, s58
	v_mov_b32_e32 v69, v172
	v_lshl_add_u64 v[68:69], v[68:69], 1, v[128:129]
	s_waitcnt lgkmcnt(1)
	global_store_dwordx4 v[68:69], v[236:239], off nt
	v_add_u32_e32 v68, 0xe00, v137
	v_ashrrev_i32_e32 v69, 5, v68
	v_lshl_add_u32 v90, v69, 9, v141
	v_ashrrev_i32_e32 v68, 4, v68
	v_and_b32_e32 v91, 0xffffff80, v68
	v_add_u32_e32 v68, s16, v91
	v_and_b32_e32 v92, 63, v69
	v_or_b32_e32 v68, v68, v92
	v_mul_lo_u32 v68, v68, s58
	v_mov_b32_e32 v69, v172
	v_lshl_add_u64 v[68:69], v[68:69], 1, v[128:129]
	s_waitcnt lgkmcnt(0)
	global_store_dwordx4 v[68:69], v[240:243], off nt
	s_waitcnt lgkmcnt(0)
	s_barrier
; template <int EPI>
; __device__ __forceinline__ void gemm_phase(const Params& p, const u16* __restrict__ A, const u16* __restrict__ Bt, int K, int nN,
;                            u16* __restrict__ Cout, int ldc) {
;     ...
; #pragma unroll
;       for (int half = 0; half < 2; ++half) {
; #pragma unroll
;         for (int mm = 0; mm < 4; ++mm) {
;           const int m = half * 4 + mm;
; #pragma unroll
;           for (int j = 0; j < 4; ++j) {
;             float rs = 1.f;
;             if (EPI == EPI_WIN) rs = rsl[wr * 128 + m * 16 + fqe * 4 + j];
;             u16* d = stg + (wr * 64 + mm * 16 + fqe * 4 + j) * 256 + (fre & 7);
; #pragma unroll
;             for (int n = 0; n < 4; ++n) {
;               const int chunk = (wc * 8 + n * 2 + (fre >> 3)) ^ (fqe << 1);
;               d[chunk * 8] = f2bf(acc[m][n][j] * rs);
;             }
;           }
;           __builtin_amdgcn_sched_barrier(0);
;         }
;         __syncthreads();
	ds_read_b128 v[64:67], v131 offset:256
	s_waitcnt lgkmcnt(0)
	v_mul_f32_e32 v48, v48, v64
	v_cvt_pk_bf16_f32 v48, v48, s0
	v_mul_f32_e32 v56, v56, v64
	v_mul_f32_e32 v52, v52, v64
	ds_write_b16 v112, v48
	v_mul_f32_e32 v48, v61, v65
	v_cvt_pk_bf16_f32 v56, v56, s0
	v_cvt_pk_bf16_f32 v52, v52, s0
	v_cvt_pk_bf16_f32 v48, v48, s0
	v_mul_f32_e32 v60, v60, v64
	ds_write_b16 v120, v56
	ds_write_b16 v116, v52
	ds_write_b16 v124, v48 offset:512
	v_mul_f32_e32 v48, v57, v65
	v_cvt_pk_bf16_f32 v60, v60, s0
	v_cvt_pk_bf16_f32 v48, v48, s0
	ds_write_b16 v124, v60
	ds_write_b16 v120, v48 offset:512
	v_mul_f32_e32 v48, v53, v65
	v_cvt_pk_bf16_f32 v48, v48, s0
	ds_write_b16 v116, v48 offset:512
	v_mul_f32_e32 v48, v49, v65
	v_cvt_pk_bf16_f32 v48, v48, s0
	ds_write_b16 v112, v48 offset:512
	v_mul_f32_e32 v48, v62, v66
	v_cvt_pk_bf16_f32 v48, v48, s0
	ds_write_b16 v124, v48 offset:1024
	v_mul_f32_e32 v48, v58, v66
	v_cvt_pk_bf16_f32 v48, v48, s0
	ds_write_b16 v120, v48 offset:1024
	v_mul_f32_e32 v48, v54, v66
	v_cvt_pk_bf16_f32 v48, v48, s0
	ds_write_b16 v116, v48 offset:1024
	v_mul_f32_e32 v48, v50, v66
	v_cvt_pk_bf16_f32 v48, v48, s0
	ds_write_b16 v112, v48 offset:1024
	v_mul_f32_e32 v48, v63, v67
	v_cvt_pk_bf16_f32 v48, v48, s0
	ds_write_b16 v124, v48 offset:1536
	v_mul_f32_e32 v48, v59, v67
	v_cvt_pk_bf16_f32 v48, v48, s0
	ds_write_b16 v120, v48 offset:1536
	v_mul_f32_e32 v48, v55, v67
	v_cvt_pk_bf16_f32 v48, v48, s0
	ds_write_b16 v116, v48 offset:1536
	v_mul_f32_e32 v48, v51, v67
	v_cvt_pk_bf16_f32 v48, v48, s0
	ds_write_b16 v112, v48 offset:1536
	ds_read_b128 v[48:51], v131 offset:320
	s_waitcnt lgkmcnt(0)
	v_mul_f32_e32 v44, v44, v48
	v_mul_f32_e32 v32, v32, v48
	v_mul_f32_e32 v40, v40, v48
	v_cvt_pk_bf16_f32 v44, v44, s0
	v_cvt_pk_bf16_f32 v32, v32, s0
	v_mul_f32_e32 v36, v36, v48
	v_cvt_pk_bf16_f32 v40, v40, s0
	ds_write_b16 v124, v44 offset:8192
	ds_write_b16 v120, v40 offset:8192
	ds_write_b16 v112, v32 offset:8192
	v_mul_f32_e32 v32, v45, v49
	v_cvt_pk_bf16_f32 v36, v36, s0
	v_cvt_pk_bf16_f32 v32, v32, s0
	ds_write_b16 v116, v36 offset:8192
	ds_write_b16 v124, v32 offset:8704
	v_mul_f32_e32 v32, v41, v49
	v_cvt_pk_bf16_f32 v32, v32, s0
	ds_write_b16 v120, v32 offset:8704
	v_mul_f32_e32 v32, v37, v49
	v_cvt_pk_bf16_f32 v32, v32, s0
	ds_write_b16 v116, v32 offset:8704
	v_mul_f32_e32 v32, v33, v49
	v_cvt_pk_bf16_f32 v32, v32, s0
	ds_write_b16 v112, v32 offset:8704
	v_mul_f32_e32 v32, v46, v50
	v_cvt_pk_bf16_f32 v32, v32, s0
	ds_write_b16 v124, v32 offset:9216
	v_mul_f32_e32 v32, v42, v50
	v_cvt_pk_bf16_f32 v32, v32, s0
	ds_write_b16 v120, v32 offset:9216
	v_mul_f32_e32 v32, v38, v50
	v_cvt_pk_bf16_f32 v32, v32, s0
	ds_write_b16 v116, v32 offset:9216
	v_mul_f32_e32 v32, v34, v50
	v_cvt_pk_bf16_f32 v32, v32, s0
	ds_write_b16 v112, v32 offset:9216
	v_mul_f32_e32 v32, v47, v51
	v_cvt_pk_bf16_f32 v32, v32, s0
	ds_write_b16 v124, v32 offset:9728
	v_mul_f32_e32 v32, v43, v51
	v_cvt_pk_bf16_f32 v32, v32, s0
	ds_write_b16 v120, v32 offset:9728
	v_mul_f32_e32 v32, v39, v51
	v_cvt_pk_bf16_f32 v32, v32, s0
	ds_write_b16 v116, v32 offset:9728
	v_mul_f32_e32 v32, v35, v51
	v_cvt_pk_bf16_f32 v32, v32, s0
	ds_write_b16 v112, v32 offset:9728
	ds_read_b128 v[32:35], v131 offset:384
	s_waitcnt lgkmcnt(0)
	v_mul_f32_e32 v28, v28, v32
	v_mul_f32_e32 v16, v16, v32
	v_mul_f32_e32 v24, v24, v32
	v_cvt_pk_bf16_f32 v28, v28, s0
	v_cvt_pk_bf16_f32 v16, v16, s0
	v_mul_f32_e32 v20, v20, v32
	v_cvt_pk_bf16_f32 v24, v24, s0
	ds_write_b16 v124, v28 offset:16384
	ds_write_b16 v120, v24 offset:16384
	ds_write_b16 v112, v16 offset:16384
	v_mul_f32_e32 v16, v29, v33
	v_cvt_pk_bf16_f32 v20, v20, s0
	v_cvt_pk_bf16_f32 v16, v16, s0
	ds_write_b16 v116, v20 offset:16384
	ds_write_b16 v124, v16 offset:16896
	v_mul_f32_e32 v16, v25, v33
	v_cvt_pk_bf16_f32 v16, v16, s0
	ds_write_b16 v120, v16 offset:16896
	v_mul_f32_e32 v16, v21, v33
	v_cvt_pk_bf16_f32 v16, v16, s0
	ds_write_b16 v116, v16 offset:16896
	v_mul_f32_e32 v16, v17, v33
	v_cvt_pk_bf16_f32 v16, v16, s0
	ds_write_b16 v112, v16 offset:16896
	v_mul_f32_e32 v16, v30, v34
	v_cvt_pk_bf16_f32 v16, v16, s0
	ds_write_b16 v124, v16 offset:17408
	v_mul_f32_e32 v16, v26, v34
	v_cvt_pk_bf16_f32 v16, v16, s0
	ds_write_b16 v120, v16 offset:17408
	v_mul_f32_e32 v16, v22, v34
	v_cvt_pk_bf16_f32 v16, v16, s0
	ds_write_b16 v116, v16 offset:17408
	v_mul_f32_e32 v16, v18, v34
	v_cvt_pk_bf16_f32 v16, v16, s0
	ds_write_b16 v112, v16 offset:17408
	v_mul_f32_e32 v16, v31, v35
	v_cvt_pk_bf16_f32 v16, v16, s0
	ds_write_b16 v124, v16 offset:17920
	v_mul_f32_e32 v16, v27, v35
	v_cvt_pk_bf16_f32 v16, v16, s0
	ds_write_b16 v120, v16 offset:17920
	v_mul_f32_e32 v16, v23, v35
	v_cvt_pk_bf16_f32 v16, v16, s0
	ds_write_b16 v116, v16 offset:17920
	v_mul_f32_e32 v16, v19, v35
	v_cvt_pk_bf16_f32 v16, v16, s0
	ds_write_b16 v112, v16 offset:17920
	ds_read_b128 v[16:19], v131 offset:448
	s_waitcnt lgkmcnt(0)
	v_mul_f32_e32 v12, v12, v16
	v_mul_f32_e32 v0, v0, v16
	v_mul_f32_e32 v8, v8, v16
	v_cvt_pk_bf16_f32 v12, v12, s0
	v_cvt_pk_bf16_f32 v0, v0, s0
	v_mul_f32_e32 v4, v4, v16
	v_cvt_pk_bf16_f32 v8, v8, s0
	ds_write_b16 v124, v12 offset:24576
	ds_write_b16 v120, v8 offset:24576
	ds_write_b16 v112, v0 offset:24576
	v_mul_f32_e32 v0, v13, v17
	v_cvt_pk_bf16_f32 v4, v4, s0
	v_cvt_pk_bf16_f32 v0, v0, s0
	ds_write_b16 v116, v4 offset:24576
	ds_write_b16 v124, v0 offset:25088
	v_mul_f32_e32 v0, v9, v17
	v_cvt_pk_bf16_f32 v0, v0, s0
	ds_write_b16 v120, v0 offset:25088
	v_mul_f32_e32 v0, v5, v17
	v_cvt_pk_bf16_f32 v0, v0, s0
	ds_write_b16 v116, v0 offset:25088
	v_mul_f32_e32 v0, v1, v17
	v_cvt_pk_bf16_f32 v0, v0, s0
	ds_write_b16 v112, v0 offset:25088
	v_mul_f32_e32 v0, v14, v18
	v_cvt_pk_bf16_f32 v0, v0, s0
	ds_write_b16 v124, v0 offset:25600
	v_mul_f32_e32 v0, v10, v18
	v_cvt_pk_bf16_f32 v0, v0, s0
	ds_write_b16 v120, v0 offset:25600
	v_mul_f32_e32 v0, v6, v18
	v_cvt_pk_bf16_f32 v0, v0, s0
	ds_write_b16 v116, v0 offset:25600
	v_mul_f32_e32 v0, v2, v18
	v_cvt_pk_bf16_f32 v0, v0, s0
	ds_write_b16 v112, v0 offset:25600
	v_mul_f32_e32 v0, v15, v19
	v_cvt_pk_bf16_f32 v0, v0, s0
	ds_write_b16 v124, v0 offset:26112
	v_mul_f32_e32 v0, v11, v19
	v_cvt_pk_bf16_f32 v0, v0, s0
	ds_write_b16 v120, v0 offset:26112
	v_mul_f32_e32 v0, v7, v19
	v_cvt_pk_bf16_f32 v0, v0, s0
	ds_write_b16 v116, v0 offset:26112
	v_mul_f32_e32 v0, v3, v19
	v_cvt_pk_bf16_f32 v0, v0, s0
	ds_write_b16 v112, v0 offset:26112
	s_waitcnt lgkmcnt(0)
	s_barrier
; template <int EPI>
; __device__ __forceinline__ void gemm_phase(const Params& p, const u16* __restrict__ A, const u16* __restrict__ Bt, int K, int nN,
;                            u16* __restrict__ Cout, int ldc) {
;     ...
; #pragma unroll
;         for (int it = 0; it < 8; ++it) {
;           const int id = it * 512 + tide, r = id >> 5, ck = id & 31;
;           const uint4 v = *(const uint4*)(stg + r * 256 + ((ck ^ (((r >> 2) & 3) << 1)) * 8));
;           const int grow = brow + (r >> 6) * 128 + half * 64 + (r & 63);
;           if (EPI == EPI_WIN) { typedef __attribute__((ext_vector_type(4))) unsigned u32x4_; const u32x4_ t_ = {v.x, v.y, v.z, v.w};
;             __builtin_nontemporal_store(t_, (u32x4_*)(Cout + (unsigned)grow * (unsigned)ldc + (unsigned)(bcol + ck * 8))); }
;           else *(uint4*)(Cout + (unsigned)grow * (unsigned)ldc + (unsigned)(bcol + ck * 8)) = v;
;         }
;         asm volatile("s_waitcnt lgkmcnt(0)" ::: "memory"); __builtin_amdgcn_s_barrier();
	s_or_b32 s2, s16, 64
	ds_read_b128 v[212:215], v130
	ds_read_b128 v[216:219], v72
	ds_read_b128 v[220:223], v75
	ds_read_b128 v[224:227], v78
	ds_read_b128 v[228:231], v81
	ds_read_b128 v[232:235], v84
	ds_read_b128 v[236:239], v87
	ds_read_b128 v[240:243], v90
	v_add_u32_e32 v4, s2, v70
	v_or_b32_e32 v4, v4, v71
	v_mul_lo_u32 v4, v4, s58
	v_mov_b32_e32 v5, v172
	v_lshl_add_u64 v[4:5], v[4:5], 1, v[128:129]
	s_waitcnt lgkmcnt(7)
	global_store_dwordx4 v[4:5], v[212:215], off nt
	v_add_u32_e32 v4, s2, v73
	v_or_b32_e32 v4, v4, v74
	v_mul_lo_u32 v4, v4, s58
	v_mov_b32_e32 v5, v172
	v_lshl_add_u64 v[4:5], v[4:5], 1, v[128:129]
	s_waitcnt lgkmcnt(6)
	global_store_dwordx4 v[4:5], v[216:219], off nt
	v_add_u32_e32 v4, s2, v76
	v_or_b32_e32 v4, v4, v77
	v_mul_lo_u32 v4, v4, s58
	v_mov_b32_e32 v5, v172
	v_lshl_add_u64 v[4:5], v[4:5], 1, v[128:129]
	s_waitcnt lgkmcnt(5)
	global_store_dwordx4 v[4:5], v[220:223], off nt
	v_add_u32_e32 v4, s2, v79
	v_or_b32_e32 v4, v4, v80
	v_mul_lo_u32 v4, v4, s58
	v_mov_b32_e32 v5, v172
	v_lshl_add_u64 v[4:5], v[4:5], 1, v[128:129]
	s_waitcnt lgkmcnt(4)
	global_store_dwordx4 v[4:5], v[224:227], off nt
	v_add_u32_e32 v4, s2, v82
	v_or_b32_e32 v4, v4, v83
	v_mul_lo_u32 v4, v4, s58
	v_mov_b32_e32 v5, v172
	v_lshl_add_u64 v[4:5], v[4:5], 1, v[128:129]
	s_waitcnt lgkmcnt(3)
	global_store_dwordx4 v[4:5], v[228:231], off nt
	v_add_u32_e32 v4, s2, v85
	v_or_b32_e32 v4, v4, v86
	v_mul_lo_u32 v4, v4, s58
	v_mov_b32_e32 v5, v172
	v_lshl_add_u64 v[4:5], v[4:5], 1, v[128:129]
	s_waitcnt lgkmcnt(2)
	global_store_dwordx4 v[4:5], v[232:235], off nt
	v_add_u32_e32 v4, s2, v88
	v_or_b32_e32 v4, v4, v89
	v_mul_lo_u32 v4, v4, s58
	v_mov_b32_e32 v5, v172
	v_lshl_add_u64 v[4:5], v[4:5], 1, v[128:129]
	s_waitcnt lgkmcnt(1)
	global_store_dwordx4 v[4:5], v[236:239], off nt
	v_add_u32_e32 v4, s2, v91
	v_or_b32_e32 v4, v4, v92
	v_mul_lo_u32 v4, v4, s58
	v_mov_b32_e32 v5, v172
	v_lshl_add_u64 v[4:5], v[4:5], 1, v[128:129]
	s_waitcnt lgkmcnt(0)
	global_store_dwordx4 v[4:5], v[240:243], off nt
	s_waitcnt lgkmcnt(0)
	s_mov_b64 s[34:35], -1
	s_and_b64 vcc, exec, s[14:15]
	s_barrier
	s_cbranch_vccnz .LBB0_881

; template <int EPI>
; __device__ __forceinline__ void gemm_phase(const Params& p, const u16* __restrict__ A, const u16* __restrict__ Bt, int K, int nN,
;                            u16* __restrict__ Cout, int ldc) {
;     ...
; #pragma unroll
;       for (int half = 0; half < 2; ++half) {
; #pragma unroll
;         for (int mm = 0; mm < 4; ++mm) {
;           const int m = half * 4 + mm;
; #pragma unroll
;           for (int j = 0; j < 4; ++j) {
;             float rs = 1.f;
;             if (EPI == EPI_WIN) rs = rsl[wr * 128 + m * 16 + fqe * 4 + j];
;             u16* d = stg + (wr * 64 + mm * 16 + fqe * 4 + j) * 256 + (fre & 7);
; #pragma unroll
;             for (int n = 0; n < 4; ++n) {
;               const int chunk = (wc * 8 + n * 2 + (fre >> 3)) ^ (fqe << 1);
;               d[chunk * 8] = f2bf(acc[m][n][j] * rs);
;             }
;           }
;           __builtin_amdgcn_sched_barrier(0);
;         }
;         __syncthreads();
.Lss_epi:
	v_mov_b32_e32 v66, v181
	v_mov_b32_e32 v112, v173
	v_mov_b32_e32 v64, v191
	s_waitcnt vmcnt(0)
	s_waitcnt vmcnt(0) lgkmcnt(0)
	s_barrier
	s_mov_b32 s0, 0x10000
	v_and_b32_e32 v65, 7, v64
	v_lshlrev_b32_e32 v67, 1, v65
	v_add_u32_e32 v114, v64, v196
	v_lshlrev_b32_e32 v113, 4, v66
	v_lshl_or_b32 v66, v66, 11, v67
	v_and_b32_e32 v118, -8, v114
	v_add3_u32 v66, v66, v195, s0
	v_bitop3_b32 v114, v114, v113, -8 bitop3:0x6c
	v_add_u32_e32 v119, 16, v118
	v_cvt_pk_bf16_f32 v67, v128, s0
	v_lshl_add_u32 v114, v114, 1, v66
	v_xor_b32_e32 v119, v119, v113
	v_add_u32_e32 v120, 32, v118
	ds_write_b16 v114, v67
	v_cvt_pk_bf16_f32 v67, v132, s0
	v_lshl_add_u32 v119, v119, 1, v66
	v_xor_b32_e32 v120, v120, v113
	v_add_u32_e32 v118, 48, v118
	ds_write_b16 v119, v67
	v_cvt_pk_bf16_f32 v67, v136, s0
	v_lshl_add_u32 v120, v120, 1, v66
	v_xor_b32_e32 v113, v118, v113
	ds_write_b16 v120, v67
	v_cvt_pk_bf16_f32 v67, v140, s0
	v_lshl_add_u32 v113, v113, 1, v66
	v_cvt_pk_bf16_f32 v66, v129, s0
	ds_write_b16 v113, v67
	ds_write_b16 v114, v66 offset:512
	v_cvt_pk_bf16_f32 v66, v133, s0
	ds_write_b16 v119, v66 offset:512
	v_cvt_pk_bf16_f32 v66, v137, s0
	ds_write_b16 v120, v66 offset:512
	v_cvt_pk_bf16_f32 v66, v141, s0
	ds_write_b16 v113, v66 offset:512
	v_cvt_pk_bf16_f32 v66, v130, s0
	ds_write_b16 v114, v66 offset:1024
	v_cvt_pk_bf16_f32 v66, v134, s0
	ds_write_b16 v119, v66 offset:1024
	v_cvt_pk_bf16_f32 v66, v138, s0
	ds_write_b16 v120, v66 offset:1024
	v_cvt_pk_bf16_f32 v66, v142, s0
	ds_write_b16 v113, v66 offset:1024
	v_cvt_pk_bf16_f32 v66, v131, s0
	v_and_b32_e32 v64, 31, v112
	v_lshrrev_b32_e32 v65, 6, v112
	ds_write_b16 v114, v66 offset:1536
	v_cvt_pk_bf16_f32 v66, v135, s0
	v_bitop3_b32 v65, v65, v64, 6 bitop3:0x6c
	ds_write_b16 v119, v66 offset:1536
	v_cvt_pk_bf16_f32 v66, v139, s0
	v_lshl_or_b32 v115, v65, 4, v188
	v_lshl_or_b32 v64, v64, 3, s28
	v_mov_b32_e32 v65, v172
	v_ashrrev_i32_e32 v116, 5, v112
	ds_write_b16 v120, v66 offset:1536
	v_cvt_pk_bf16_f32 v66, v143, s0
	v_lshl_add_u64 v[64:65], v[64:65], 1, s[2:3]
	v_lshl_add_u32 v117, v116, 9, v115
	ds_write_b16 v113, v66 offset:1536
	v_cvt_pk_bf16_f32 v66, v108, s0
	ds_write_b16 v114, v66 offset:8192
	v_cvt_pk_bf16_f32 v66, v104, s0
	ds_write_b16 v119, v66 offset:8192
	v_cvt_pk_bf16_f32 v66, v100, s0
	ds_write_b16 v120, v66 offset:8192
	v_cvt_pk_bf16_f32 v66, v96, s0
	ds_write_b16 v113, v66 offset:8192
	v_cvt_pk_bf16_f32 v66, v109, s0
	ds_write_b16 v114, v66 offset:8704
	v_cvt_pk_bf16_f32 v66, v105, s0
	ds_write_b16 v119, v66 offset:8704
	v_cvt_pk_bf16_f32 v66, v101, s0
	ds_write_b16 v120, v66 offset:8704
	v_cvt_pk_bf16_f32 v66, v97, s0
	ds_write_b16 v113, v66 offset:8704
	v_cvt_pk_bf16_f32 v66, v110, s0
	ds_write_b16 v114, v66 offset:9216
	v_cvt_pk_bf16_f32 v66, v106, s0
	ds_write_b16 v119, v66 offset:9216
	v_cvt_pk_bf16_f32 v66, v102, s0
	ds_write_b16 v120, v66 offset:9216
	v_cvt_pk_bf16_f32 v66, v98, s0
	ds_write_b16 v113, v66 offset:9216
	v_cvt_pk_bf16_f32 v66, v111, s0
	ds_write_b16 v114, v66 offset:9728
	v_cvt_pk_bf16_f32 v66, v107, s0
	ds_write_b16 v119, v66 offset:9728
	v_cvt_pk_bf16_f32 v66, v103, s0
	ds_write_b16 v120, v66 offset:9728
	v_cvt_pk_bf16_f32 v66, v99, s0
	ds_write_b16 v113, v66 offset:9728
	v_cvt_pk_bf16_f32 v66, v92, s0
	ds_write_b16 v114, v66 offset:16384
	v_cvt_pk_bf16_f32 v66, v88, s0
	ds_write_b16 v119, v66 offset:16384
	v_cvt_pk_bf16_f32 v66, v84, s0
	ds_write_b16 v120, v66 offset:16384
	v_cvt_pk_bf16_f32 v66, v80, s0
	ds_write_b16 v113, v66 offset:16384
	v_cvt_pk_bf16_f32 v66, v93, s0
	ds_write_b16 v114, v66 offset:16896
	v_cvt_pk_bf16_f32 v66, v89, s0
	ds_write_b16 v119, v66 offset:16896
	v_cvt_pk_bf16_f32 v66, v85, s0
	ds_write_b16 v120, v66 offset:16896
	v_cvt_pk_bf16_f32 v66, v81, s0
	ds_write_b16 v113, v66 offset:16896
	v_cvt_pk_bf16_f32 v66, v94, s0
	ds_write_b16 v114, v66 offset:17408
	v_cvt_pk_bf16_f32 v66, v90, s0
	ds_write_b16 v119, v66 offset:17408
	v_cvt_pk_bf16_f32 v66, v86, s0
	ds_write_b16 v120, v66 offset:17408
	v_cvt_pk_bf16_f32 v66, v82, s0
	ds_write_b16 v113, v66 offset:17408
	v_cvt_pk_bf16_f32 v66, v95, s0
	ds_write_b16 v114, v66 offset:17920
	v_cvt_pk_bf16_f32 v66, v91, s0
	ds_write_b16 v119, v66 offset:17920
	v_cvt_pk_bf16_f32 v66, v87, s0
	ds_write_b16 v120, v66 offset:17920
	v_cvt_pk_bf16_f32 v66, v83, s0
	ds_write_b16 v113, v66 offset:17920
	v_cvt_pk_bf16_f32 v66, v76, s0
	ds_write_b16 v114, v66 offset:24576
	v_cvt_pk_bf16_f32 v66, v72, s0
	ds_write_b16 v119, v66 offset:24576
	v_cvt_pk_bf16_f32 v66, v68, s0
	ds_write_b16 v120, v66 offset:24576
	v_cvt_pk_bf16_f32 v66, v148, s0
	ds_write_b16 v113, v66 offset:24576
	v_cvt_pk_bf16_f32 v66, v77, s0
	ds_write_b16 v114, v66 offset:25088
	v_cvt_pk_bf16_f32 v66, v73, s0
	ds_write_b16 v119, v66 offset:25088
	v_cvt_pk_bf16_f32 v66, v69, s0
	ds_write_b16 v120, v66 offset:25088
	v_cvt_pk_bf16_f32 v66, v149, s0
	ds_write_b16 v113, v66 offset:25088
	v_cvt_pk_bf16_f32 v66, v78, s0
	ds_write_b16 v114, v66 offset:25600
	v_cvt_pk_bf16_f32 v66, v74, s0
	ds_write_b16 v119, v66 offset:25600
	v_cvt_pk_bf16_f32 v66, v70, s0
	ds_write_b16 v120, v66 offset:25600
	v_cvt_pk_bf16_f32 v66, v150, s0
	ds_write_b16 v113, v66 offset:25600
	v_cvt_pk_bf16_f32 v66, v79, s0
	ds_write_b16 v114, v66 offset:26112
	v_cvt_pk_bf16_f32 v66, v75, s0
	ds_write_b16 v119, v66 offset:26112
	v_cvt_pk_bf16_f32 v66, v71, s0
	ds_write_b16 v120, v66 offset:26112
	v_cvt_pk_bf16_f32 v66, v151, s0
	ds_write_b16 v113, v66 offset:26112
	v_lshrrev_b32_e32 v70, 4, v112
	s_waitcnt lgkmcnt(0)
	s_barrier
; template <int EPI>
; __device__ __forceinline__ void gemm_phase(const Params& p, const u16* __restrict__ A, const u16* __restrict__ Bt, int K, int nN,
;                            u16* __restrict__ Cout, int ldc) {
;     ...
; #pragma unroll
;         for (int it = 0; it < 8; ++it) {
;           const int id = it * 512 + tide, r = id >> 5, ck = id & 31;
;           const uint4 v = *(const uint4*)(stg + r * 256 + ((ck ^ (((r >> 2) & 3) << 1)) * 8));
;           const int grow = brow + (r >> 6) * 128 + half * 64 + (r & 63);
;           if (EPI == EPI_WIN) { typedef __attribute__((ext_vector_type(4))) unsigned u32x4_; const u32x4_ t_ = {v.x, v.y, v.z, v.w};
;             __builtin_nontemporal_store(t_, (u32x4_*)(Cout + (unsigned)grow * (unsigned)ldc + (unsigned)(bcol + ck * 8))); }
;           else *(uint4*)(Cout + (unsigned)grow * (unsigned)ldc + (unsigned)(bcol + ck * 8)) = v;
;         }
;         asm volatile("s_waitcnt lgkmcnt(0)" ::: "memory"); __builtin_amdgcn_s_barrier();
	ds_read_b128 v[212:215], v117
	v_add_u32_e32 v244, 0x200, v112
	v_ashrrev_i32_e32 v245, 5, v244
	v_lshl_add_u32 v244, v245, 9, v115
	ds_read_b128 v[216:219], v244
	v_add_u32_e32 v244, 0x400, v112
	v_ashrrev_i32_e32 v245, 5, v244
	v_lshl_add_u32 v244, v245, 9, v115
	ds_read_b128 v[220:223], v244
	v_add_u32_e32 v244, 0x600, v112
	v_ashrrev_i32_e32 v245, 5, v244
	v_lshl_add_u32 v244, v245, 9, v115
	ds_read_b128 v[224:227], v244
	v_add_u32_e32 v244, 0x800, v112
	v_ashrrev_i32_e32 v245, 5, v244
	v_lshl_add_u32 v244, v245, 9, v115
	ds_read_b128 v[228:231], v244
	v_add_u32_e32 v244, 0xa00, v112
	v_ashrrev_i32_e32 v245, 5, v244
	v_lshl_add_u32 v244, v245, 9, v115
	ds_read_b128 v[232:235], v244
	v_add_u32_e32 v244, 0xc00, v112
	v_ashrrev_i32_e32 v245, 5, v244
	v_lshl_add_u32 v244, v245, 9, v115
	ds_read_b128 v[236:239], v244
	v_add_u32_e32 v244, 0xe00, v112
	v_ashrrev_i32_e32 v245, 5, v244
	v_lshl_add_u32 v244, v245, 9, v115
	ds_read_b128 v[240:243], v244
	v_and_b32_e32 v72, 0x3fff80, v70
	v_add_u32_e32 v70, s27, v72
	v_and_b32_e32 v73, 63, v116
	v_or_b32_e32 v70, v70, v73
	v_lshlrev_b32_e32 v70, 10, v70
	v_mov_b32_e32 v71, v172
	v_lshl_add_u64 v[70:71], v[70:71], 1, v[64:65]
	s_waitcnt lgkmcnt(7)
	global_store_dwordx4 v[70:71], v[212:215], off
	v_add_u32_e32 v70, 0x200, v112
	v_ashrrev_i32_e32 v71, 5, v70
	v_lshl_add_u32 v74, v71, 9, v115
	v_lshrrev_b32_e32 v70, 4, v70
	v_and_b32_e32 v75, 0x3fff80, v70
	v_add_u32_e32 v70, s27, v75
	v_and_b32_e32 v76, 63, v71
	v_or_b32_e32 v70, v70, v76
	v_lshlrev_b32_e32 v70, 10, v70
	v_mov_b32_e32 v71, v172
	v_lshl_add_u64 v[70:71], v[70:71], 1, v[64:65]
	s_waitcnt lgkmcnt(6)
	global_store_dwordx4 v[70:71], v[216:219], off
	v_add_u32_e32 v70, 0x400, v112
	v_ashrrev_i32_e32 v71, 5, v70
	v_lshl_add_u32 v77, v71, 9, v115
	v_lshrrev_b32_e32 v70, 4, v70
	v_and_b32_e32 v78, 0x3fff80, v70
	v_add_u32_e32 v70, s27, v78
	v_and_b32_e32 v79, 63, v71
	v_or_b32_e32 v70, v70, v79
	v_lshlrev_b32_e32 v70, 10, v70
	v_mov_b32_e32 v71, v172
	v_lshl_add_u64 v[70:71], v[70:71], 1, v[64:65]
	s_waitcnt lgkmcnt(5)
	global_store_dwordx4 v[70:71], v[220:223], off
	v_add_u32_e32 v70, 0x600, v112
	v_ashrrev_i32_e32 v71, 5, v70
	v_lshl_add_u32 v80, v71, 9, v115
	v_lshrrev_b32_e32 v70, 4, v70
	v_and_b32_e32 v81, 0x3fff80, v70
	v_add_u32_e32 v70, s27, v81
	v_and_b32_e32 v82, 63, v71
	v_or_b32_e32 v70, v70, v82
	v_lshlrev_b32_e32 v70, 10, v70
	v_mov_b32_e32 v71, v172
	v_lshl_add_u64 v[70:71], v[70:71], 1, v[64:65]
	s_waitcnt lgkmcnt(4)
	global_store_dwordx4 v[70:71], v[224:227], off
	v_add_u32_e32 v70, 0x800, v112
	v_ashrrev_i32_e32 v71, 5, v70
	v_lshl_add_u32 v83, v71, 9, v115
	v_lshrrev_b32_e32 v70, 4, v70
	v_and_b32_e32 v84, 0x3fff80, v70
	v_add_u32_e32 v70, s27, v84
	v_and_b32_e32 v85, 63, v71
	v_or_b32_e32 v70, v70, v85
	v_lshlrev_b32_e32 v70, 10, v70
	v_mov_b32_e32 v71, v172
	v_lshl_add_u64 v[70:71], v[70:71], 1, v[64:65]
	s_waitcnt lgkmcnt(3)
	global_store_dwordx4 v[70:71], v[228:231], off
	v_add_u32_e32 v70, 0xa00, v112
	v_ashrrev_i32_e32 v71, 5, v70
	v_lshl_add_u32 v86, v71, 9, v115
	v_lshrrev_b32_e32 v70, 4, v70
	v_and_b32_e32 v87, 0x3fff80, v70
	v_add_u32_e32 v70, s27, v87
	v_and_b32_e32 v88, 63, v71
	v_or_b32_e32 v70, v70, v88
	v_lshlrev_b32_e32 v70, 10, v70
	v_mov_b32_e32 v71, v172
	v_lshl_add_u64 v[70:71], v[70:71], 1, v[64:65]
	s_waitcnt lgkmcnt(2)
	global_store_dwordx4 v[70:71], v[232:235], off
	v_add_u32_e32 v70, 0xc00, v112
	v_ashrrev_i32_e32 v71, 5, v70
	v_lshl_add_u32 v89, v71, 9, v115
	v_lshrrev_b32_e32 v70, 4, v70
	v_and_b32_e32 v90, 0x3fff80, v70
	v_add_u32_e32 v70, s27, v90
	v_and_b32_e32 v91, 63, v71
	v_or_b32_e32 v70, v70, v91
	v_lshlrev_b32_e32 v70, 10, v70
	v_mov_b32_e32 v71, v172
	v_lshl_add_u64 v[70:71], v[70:71], 1, v[64:65]
	s_waitcnt lgkmcnt(1)
	global_store_dwordx4 v[70:71], v[236:239], off
	v_add_u32_e32 v70, 0xe00, v112
	v_ashrrev_i32_e32 v71, 5, v70
	v_lshl_add_u32 v92, v71, 9, v115
	v_lshrrev_b32_e32 v70, 4, v70
	v_and_b32_e32 v93, 0x3fff80, v70
	v_add_u32_e32 v70, s27, v93
	v_and_b32_e32 v94, 63, v71
	v_or_b32_e32 v70, v70, v94
	v_lshlrev_b32_e32 v70, 10, v70
	v_mov_b32_e32 v71, v172
	v_lshl_add_u64 v[70:71], v[70:71], 1, v[64:65]
	s_waitcnt lgkmcnt(0)
	global_store_dwordx4 v[70:71], v[240:243], off
	v_cvt_pk_bf16_f32 v48, v48, s0
	s_waitcnt lgkmcnt(0)
	s_barrier
; template <int EPI>
; __device__ __forceinline__ void gemm_phase(const Params& p, const u16* __restrict__ A, const u16* __restrict__ Bt, int K, int nN,
;                            u16* __restrict__ Cout, int ldc) {
;     ...
; #pragma unroll
;       for (int half = 0; half < 2; ++half) {
; #pragma unroll
;         for (int mm = 0; mm < 4; ++mm) {
;           const int m = half * 4 + mm;
; #pragma unroll
;           for (int j = 0; j < 4; ++j) {
;             float rs = 1.f;
;             if (EPI == EPI_WIN) rs = rsl[wr * 128 + m * 16 + fqe * 4 + j];
;             u16* d = stg + (wr * 64 + mm * 16 + fqe * 4 + j) * 256 + (fre & 7);
; #pragma unroll
;             for (int n = 0; n < 4; ++n) {
;               const int chunk = (wc * 8 + n * 2 + (fre >> 3)) ^ (fqe << 1);
;               d[chunk * 8] = f2bf(acc[m][n][j] * rs);
;             }
;           }
;           __builtin_amdgcn_sched_barrier(0);
;         }
;         __syncthreads();
; #pragma unroll
;         for (int it = 0; it < 8; ++it) {
;           const int id = it * 512 + tide, r = id >> 5, ck = id & 31;
;           const uint4 v = *(const uint4*)(stg + r * 256 + ((ck ^ (((r >> 2) & 3) << 1)) * 8));
;           const int grow = brow + (r >> 6) * 128 + half * 64 + (r & 63);
;           if (EPI == EPI_WIN) { typedef __attribute__((ext_vector_type(4))) unsigned u32x4_; const u32x4_ t_ = {v.x, v.y, v.z, v.w};
;             __builtin_nontemporal_store(t_, (u32x4_*)(Cout + (unsigned)grow * (unsigned)ldc + (unsigned)(bcol + ck * 8))); }
;           else *(uint4*)(Cout + (unsigned)grow * (unsigned)ldc + (unsigned)(bcol + ck * 8)) = v;
;         }
;         asm volatile("s_waitcnt lgkmcnt(0)" ::: "memory"); __builtin_amdgcn_s_barrier();
	v_cvt_pk_bf16_f32 v56, v56, s0
	v_cvt_pk_bf16_f32 v52, v52, s0
	ds_write_b16 v113, v48
	v_cvt_pk_bf16_f32 v48, v61, s0
	v_cvt_pk_bf16_f32 v60, v60, s0
	ds_write_b16 v119, v56
	ds_write_b16 v120, v52
	ds_write_b16 v114, v48 offset:512
	v_cvt_pk_bf16_f32 v48, v57, s0
	ds_write_b16 v114, v60
	ds_write_b16 v119, v48 offset:512
	v_cvt_pk_bf16_f32 v48, v53, s0
	ds_write_b16 v120, v48 offset:512
	v_cvt_pk_bf16_f32 v48, v49, s0
	ds_write_b16 v113, v48 offset:512
	v_cvt_pk_bf16_f32 v48, v62, s0
	ds_write_b16 v114, v48 offset:1024
	v_cvt_pk_bf16_f32 v48, v58, s0
	ds_write_b16 v119, v48 offset:1024
	v_cvt_pk_bf16_f32 v48, v54, s0
	ds_write_b16 v120, v48 offset:1024
	v_cvt_pk_bf16_f32 v48, v50, s0
	ds_write_b16 v113, v48 offset:1024
	v_cvt_pk_bf16_f32 v48, v63, s0
	ds_write_b16 v114, v48 offset:1536
	v_cvt_pk_bf16_f32 v48, v59, s0
	ds_write_b16 v119, v48 offset:1536
	v_cvt_pk_bf16_f32 v48, v55, s0
	ds_write_b16 v120, v48 offset:1536
	v_cvt_pk_bf16_f32 v48, v51, s0
	ds_write_b16 v113, v48 offset:1536
	v_cvt_pk_bf16_f32 v32, v32, s0
	v_cvt_pk_bf16_f32 v40, v40, s0
	v_cvt_pk_bf16_f32 v36, v36, s0
	ds_write_b16 v113, v32 offset:8192
	v_cvt_pk_bf16_f32 v32, v45, s0
	v_cvt_pk_bf16_f32 v44, v44, s0
	ds_write_b16 v119, v40 offset:8192
	ds_write_b16 v120, v36 offset:8192
	ds_write_b16 v114, v32 offset:8704
	v_cvt_pk_bf16_f32 v32, v41, s0
	ds_write_b16 v114, v44 offset:8192
	ds_write_b16 v119, v32 offset:8704
	v_cvt_pk_bf16_f32 v32, v37, s0
	ds_write_b16 v120, v32 offset:8704
	v_cvt_pk_bf16_f32 v32, v33, s0
	ds_write_b16 v113, v32 offset:8704
	v_cvt_pk_bf16_f32 v32, v46, s0
	ds_write_b16 v114, v32 offset:9216
	v_cvt_pk_bf16_f32 v32, v42, s0
	ds_write_b16 v119, v32 offset:9216
	v_cvt_pk_bf16_f32 v32, v38, s0
	ds_write_b16 v120, v32 offset:9216
	v_cvt_pk_bf16_f32 v32, v34, s0
	ds_write_b16 v113, v32 offset:9216
	v_cvt_pk_bf16_f32 v32, v47, s0
	ds_write_b16 v114, v32 offset:9728
	v_cvt_pk_bf16_f32 v32, v43, s0
	ds_write_b16 v119, v32 offset:9728
	v_cvt_pk_bf16_f32 v32, v39, s0
	ds_write_b16 v120, v32 offset:9728
	v_cvt_pk_bf16_f32 v32, v35, s0
	ds_write_b16 v113, v32 offset:9728
	v_cvt_pk_bf16_f32 v16, v16, s0
	v_cvt_pk_bf16_f32 v24, v24, s0
	v_cvt_pk_bf16_f32 v20, v20, s0
	ds_write_b16 v113, v16 offset:16384
	v_cvt_pk_bf16_f32 v16, v29, s0
	v_cvt_pk_bf16_f32 v28, v28, s0
	ds_write_b16 v119, v24 offset:16384
	ds_write_b16 v120, v20 offset:16384
	ds_write_b16 v114, v16 offset:16896
	v_cvt_pk_bf16_f32 v16, v25, s0
	ds_write_b16 v114, v28 offset:16384
	ds_write_b16 v119, v16 offset:16896
	v_cvt_pk_bf16_f32 v16, v21, s0
	ds_write_b16 v120, v16 offset:16896
	v_cvt_pk_bf16_f32 v16, v17, s0
	ds_write_b16 v113, v16 offset:16896
	v_cvt_pk_bf16_f32 v16, v30, s0
	ds_write_b16 v114, v16 offset:17408
	v_cvt_pk_bf16_f32 v16, v26, s0
	ds_write_b16 v119, v16 offset:17408
	v_cvt_pk_bf16_f32 v16, v22, s0
	ds_write_b16 v120, v16 offset:17408
	v_cvt_pk_bf16_f32 v16, v18, s0
	ds_write_b16 v113, v16 offset:17408
	v_cvt_pk_bf16_f32 v16, v31, s0
	ds_write_b16 v114, v16 offset:17920
	v_cvt_pk_bf16_f32 v16, v27, s0
	ds_write_b16 v119, v16 offset:17920
	v_cvt_pk_bf16_f32 v16, v23, s0
	ds_write_b16 v120, v16 offset:17920
	v_cvt_pk_bf16_f32 v16, v19, s0
	ds_write_b16 v113, v16 offset:17920
	v_cvt_pk_bf16_f32 v0, v0, s0
	v_cvt_pk_bf16_f32 v8, v8, s0
	v_cvt_pk_bf16_f32 v4, v4, s0
	ds_write_b16 v113, v0 offset:24576
	v_cvt_pk_bf16_f32 v0, v13, s0
	v_cvt_pk_bf16_f32 v12, v12, s0
	ds_write_b16 v119, v8 offset:24576
	ds_write_b16 v120, v4 offset:24576
	ds_write_b16 v114, v0 offset:25088
	v_cvt_pk_bf16_f32 v0, v9, s0
	ds_write_b16 v114, v12 offset:24576
	ds_write_b16 v119, v0 offset:25088
	v_cvt_pk_bf16_f32 v0, v5, s0
	ds_write_b16 v120, v0 offset:25088
	v_cvt_pk_bf16_f32 v0, v1, s0
	ds_write_b16 v113, v0 offset:25088
	v_cvt_pk_bf16_f32 v0, v14, s0
	ds_write_b16 v114, v0 offset:25600
	v_cvt_pk_bf16_f32 v0, v10, s0
	ds_write_b16 v119, v0 offset:25600
	v_cvt_pk_bf16_f32 v0, v6, s0
	ds_write_b16 v120, v0 offset:25600
	v_cvt_pk_bf16_f32 v0, v2, s0
	ds_write_b16 v113, v0 offset:25600
	v_cvt_pk_bf16_f32 v0, v15, s0
	ds_write_b16 v114, v0 offset:26112
	v_cvt_pk_bf16_f32 v0, v11, s0
	ds_write_b16 v119, v0 offset:26112
	v_cvt_pk_bf16_f32 v0, v7, s0
	ds_write_b16 v120, v0 offset:26112
	v_cvt_pk_bf16_f32 v0, v3, s0
	ds_write_b16 v113, v0 offset:26112
	s_waitcnt lgkmcnt(0)
	s_barrier
	s_or_b32 s0, s27, 64
	ds_read_b128 v[212:215], v117
	ds_read_b128 v[216:219], v74
	ds_read_b128 v[220:223], v77
	ds_read_b128 v[224:227], v80
	ds_read_b128 v[228:231], v83
	ds_read_b128 v[232:235], v86
	ds_read_b128 v[236:239], v89
	ds_read_b128 v[240:243], v92
	v_add_u32_e32 v4, s0, v72
	v_or_b32_e32 v4, v4, v73
	v_lshlrev_b32_e32 v4, 10, v4
	v_mov_b32_e32 v5, v172
	v_lshl_add_u64 v[4:5], v[4:5], 1, v[64:65]
	s_waitcnt lgkmcnt(7)
	global_store_dwordx4 v[4:5], v[212:215], off
	v_add_u32_e32 v4, s0, v75
	v_or_b32_e32 v4, v4, v76
	v_lshlrev_b32_e32 v4, 10, v4
	v_mov_b32_e32 v5, v172
	v_lshl_add_u64 v[4:5], v[4:5], 1, v[64:65]
	s_waitcnt lgkmcnt(6)
	global_store_dwordx4 v[4:5], v[216:219], off
	v_add_u32_e32 v4, s0, v78
	v_or_b32_e32 v4, v4, v79
	v_lshlrev_b32_e32 v4, 10, v4
	v_mov_b32_e32 v5, v172
	v_lshl_add_u64 v[4:5], v[4:5], 1, v[64:65]
	s_waitcnt lgkmcnt(5)
	global_store_dwordx4 v[4:5], v[220:223], off
	v_add_u32_e32 v4, s0, v81
	v_or_b32_e32 v4, v4, v82
	v_lshlrev_b32_e32 v4, 10, v4
	v_mov_b32_e32 v5, v172
	v_lshl_add_u64 v[4:5], v[4:5], 1, v[64:65]
	s_waitcnt lgkmcnt(4)
	global_store_dwordx4 v[4:5], v[224:227], off
	v_add_u32_e32 v4, s0, v84
	v_or_b32_e32 v4, v4, v85
	v_lshlrev_b32_e32 v4, 10, v4
	v_mov_b32_e32 v5, v172
	v_lshl_add_u64 v[4:5], v[4:5], 1, v[64:65]
	s_waitcnt lgkmcnt(3)
	global_store_dwordx4 v[4:5], v[228:231], off
	v_add_u32_e32 v4, s0, v87
	v_or_b32_e32 v4, v4, v88
	v_lshlrev_b32_e32 v4, 10, v4
	v_mov_b32_e32 v5, v172
	v_lshl_add_u64 v[4:5], v[4:5], 1, v[64:65]
	s_waitcnt lgkmcnt(2)
	global_store_dwordx4 v[4:5], v[232:235], off
	v_add_u32_e32 v4, s0, v90
	v_or_b32_e32 v4, v4, v91
	v_lshlrev_b32_e32 v4, 10, v4
	v_mov_b32_e32 v5, v172
	v_lshl_add_u64 v[4:5], v[4:5], 1, v[64:65]
	s_waitcnt lgkmcnt(1)
	global_store_dwordx4 v[4:5], v[236:239], off
	v_add_u32_e32 v4, s0, v93
	v_or_b32_e32 v4, v4, v94
	v_lshlrev_b32_e32 v4, 10, v4
	v_mov_b32_e32 v5, v172
	v_lshl_add_u64 v[4:5], v[4:5], 1, v[64:65]
	s_waitcnt lgkmcnt(0)
	global_store_dwordx4 v[4:5], v[240:243], off
	s_waitcnt lgkmcnt(0)
	s_mov_b64 s[0:1], -1
	s_and_b64 vcc, exec, s[4:5]
	s_barrier
	s_cbranch_vccnz .LBB0_1122
